# ctx10: layer-1 context-row in-proj K loop deep-prefetched (48 loads in flight, same MFMA order), placed with zero displacement of other code; on top of xtop
# speedup vs baseline: 1.0078x; 1.0078x over previous
; __device__ __forceinline__ unsigned cvt_pk_bf16(float lo, float hi) { unsigned r; asm volatile("v_cvt_pk_bf16_f32 %0, %1, %2" : "=v"(r) : "v"(lo), "v"(hi)); return r; }
; template <int ph>
; __device__ __forceinline__ void run_phase(KPtr kp, unsigned char* shm) {
;     ...
;                 for (int it = c * 8 + (tq >> 6); it < 2048; it += G * 8) { const int tr = it >> 6, tc = it & 63;
;                     const bf16_t* ap = HB + (size_t)(MX + tr * 16 + r) * DM + q * 8; const bf16_t* bp = WT + (size_t)(C_U + tc * 16 + r) * DM + q * 8; f32x4 a4 = (f32x4){0.f, 0.f, 0.f, 0.f};
; #pragma unroll 8
;                     for (int ks = 0; ks < 64; ++ks) a4 = __builtin_amdgcn_mfma_f32_16x16x32_bf16(*(const bf16x8*)(ap + ks * 32), *(const bf16x8*)(bp + ks * 32), a4, 0, 0, 0);
; #pragma unroll
;                     for (int i = 0; i < 4; ++i) po[E_PU + (size_t)(MX + tr * 16 + q * 4 + i) * 1024 + tc * 16 + r] = (bf16_t)(cvt_pk_bf16(a4[i], 0.f) & 0xffffu); }
.LBB0_1081:
	v_add_co_u32_e32 v56, vcc, 0x120d8000, v14
	s_nop 1
	v_addc_co_u32_e32 v57, vcc, 0, v15, vcc
	v_add_co_u32_e32 v58, vcc, 0x7e22000, v12
	s_nop 1
	v_addc_co_u32_e32 v59, vcc, 0, v13, vcc
	global_load_dwordx4 v[60:63], v[56:57], off
	global_load_dwordx4 v[64:67], v[58:59], off
	global_load_dwordx4 v[68:71], v[56:57], off offset:64
	global_load_dwordx4 v[72:75], v[58:59], off offset:64
	global_load_dwordx4 v[76:79], v[56:57], off offset:128
	global_load_dwordx4 v[80:83], v[58:59], off offset:128
	global_load_dwordx4 v[84:87], v[56:57], off offset:192
	global_load_dwordx4 v[88:91], v[58:59], off offset:192
	global_load_dwordx4 v[92:95], v[56:57], off offset:256
	global_load_dwordx4 v[96:99], v[58:59], off offset:256
	global_load_dwordx4 v[100:103], v[56:57], off offset:320
	global_load_dwordx4 v[104:107], v[58:59], off offset:320
	global_load_dwordx4 v[108:111], v[56:57], off offset:384
	global_load_dwordx4 v[112:115], v[58:59], off offset:384
	global_load_dwordx4 v[116:119], v[56:57], off offset:448
	global_load_dwordx4 v[120:123], v[58:59], off offset:448
	global_load_dwordx4 v[124:127], v[56:57], off offset:512
	global_load_dwordx4 v[128:131], v[58:59], off offset:512
	global_load_dwordx4 v[132:135], v[56:57], off offset:576
	global_load_dwordx4 v[136:139], v[58:59], off offset:576
	global_load_dwordx4 v[140:143], v[56:57], off offset:640
	global_load_dwordx4 v[144:147], v[58:59], off offset:640
	global_load_dwordx4 v[148:151], v[56:57], off offset:704
	global_load_dwordx4 v[152:155], v[58:59], off offset:704
	global_load_dwordx4 v[156:159], v[56:57], off offset:768
	global_load_dwordx4 v[160:163], v[58:59], off offset:768
	global_load_dwordx4 v[164:167], v[56:57], off offset:832
	global_load_dwordx4 v[168:171], v[58:59], off offset:832
	global_load_dwordx4 v[172:175], v[56:57], off offset:896
	global_load_dwordx4 v[176:179], v[58:59], off offset:896
	global_load_dwordx4 v[180:183], v[56:57], off offset:960
	global_load_dwordx4 v[184:187], v[58:59], off offset:960
	s_branch .Lc10_body
.Lc10_ret:
	v_or_b32_e32 v12, v6, v17
	v_lshlrev_b32_e32 v6, 5, v1
	v_and_b32_e32 v6, 0x7e0, v6
	v_ashrrev_i32_e32 v13, 31, v12
	v_lshl_add_u64 v[14:15], v[8:9], 0, v[6:7]
	v_lshlrev_b64 v[20:21], 11, v[12:13]
	v_cvt_pk_bf16_f32 v2, v2, v7
	v_lshl_add_u64 v[20:21], v[14:15], 0, v[20:21]
	global_store_short v[20:21], v2, off
	v_or_b32_e32 v2, 1, v12
	v_cvt_pk_bf16_f32 v6, v3, v7
	v_ashrrev_i32_e32 v3, 31, v2
	v_lshlrev_b64 v[2:3], 11, v[2:3]
	v_lshl_add_u64 v[2:3], v[14:15], 0, v[2:3]
	global_store_short v[2:3], v6, off
	v_or_b32_e32 v2, 2, v12
	v_ashrrev_i32_e32 v3, 31, v2
	v_lshlrev_b64 v[2:3], 11, v[2:3]
	v_lshl_add_u64 v[2:3], v[14:15], 0, v[2:3]
	v_cvt_pk_bf16_f32 v4, v4, v7
	global_store_short v[2:3], v4, off
	v_or_b32_e32 v2, 3, v12
	v_ashrrev_i32_e32 v3, 31, v2
	v_add_u32_e32 v1, s2, v1
	v_lshlrev_b64 v[2:3], 11, v[2:3]
	v_cmp_lt_i32_e32 vcc, s11, v1
	v_lshl_add_u64 v[2:3], v[14:15], 0, v[2:3]
	s_or_b64 s[8:9], vcc, s[8:9]
	v_add_u32_e32 v18, s3, v18
	v_cvt_pk_bf16_f32 v4, v5, v7
	global_store_short v[2:3], v4, off
	s_andn2_b64 exec, exec, s[8:9]
	s_cbranch_execnz .LBB0_1080

; template <int ph>
; __device__ __forceinline__ void run_phase(KPtr kp, unsigned char* shm) {
;     ...
; #pragma unroll 8
;                     for (int ks = 0; ks < 64; ++ks) a4 = __builtin_amdgcn_mfma_f32_16x16x32_bf16(*(const bf16x8*)(ap + ks * 32), *(const bf16x8*)(bp + ks * 32), a4, 0, 0, 0);
.Lc10_body:
	global_load_dwordx4 v[188:191], v[56:57], off offset:1024
	global_load_dwordx4 v[192:195], v[58:59], off offset:1024
	global_load_dwordx4 v[196:199], v[56:57], off offset:1088
	global_load_dwordx4 v[200:203], v[58:59], off offset:1088
	global_load_dwordx4 v[204:207], v[56:57], off offset:1152
	global_load_dwordx4 v[208:211], v[58:59], off offset:1152
	global_load_dwordx4 v[212:215], v[56:57], off offset:1216
	global_load_dwordx4 v[216:219], v[58:59], off offset:1216
	global_load_dwordx4 v[220:223], v[56:57], off offset:1280
	global_load_dwordx4 v[224:227], v[58:59], off offset:1280
	global_load_dwordx4 v[228:231], v[56:57], off offset:1344
	global_load_dwordx4 v[232:235], v[58:59], off offset:1344
	global_load_dwordx4 v[236:239], v[56:57], off offset:1408
	global_load_dwordx4 v[240:243], v[58:59], off offset:1408
	global_load_dwordx4 v[244:247], v[56:57], off offset:1472
	global_load_dwordx4 v[248:251], v[58:59], off offset:1472
	s_waitcnt vmcnt(46)
	v_mfma_f32_16x16x32_bf16 v[2:5], v[60:63], v[64:67], v[2:5]
	global_load_dwordx4 v[60:63], v[56:57], off offset:1536
	global_load_dwordx4 v[64:67], v[58:59], off offset:1536
	s_waitcnt vmcnt(46)
	v_mfma_f32_16x16x32_bf16 v[2:5], v[68:71], v[72:75], v[2:5]
	global_load_dwordx4 v[68:71], v[56:57], off offset:1600
	global_load_dwordx4 v[72:75], v[58:59], off offset:1600
	s_waitcnt vmcnt(46)
	v_mfma_f32_16x16x32_bf16 v[2:5], v[76:79], v[80:83], v[2:5]
	global_load_dwordx4 v[76:79], v[56:57], off offset:1664
	global_load_dwordx4 v[80:83], v[58:59], off offset:1664
	s_waitcnt vmcnt(46)
	v_mfma_f32_16x16x32_bf16 v[2:5], v[84:87], v[88:91], v[2:5]
	global_load_dwordx4 v[84:87], v[56:57], off offset:1728
	global_load_dwordx4 v[88:91], v[58:59], off offset:1728
	s_waitcnt vmcnt(46)
	v_mfma_f32_16x16x32_bf16 v[2:5], v[92:95], v[96:99], v[2:5]
	global_load_dwordx4 v[92:95], v[56:57], off offset:1792
	global_load_dwordx4 v[96:99], v[58:59], off offset:1792
	s_waitcnt vmcnt(46)
	v_mfma_f32_16x16x32_bf16 v[2:5], v[100:103], v[104:107], v[2:5]
	global_load_dwordx4 v[100:103], v[56:57], off offset:1856
	global_load_dwordx4 v[104:107], v[58:59], off offset:1856
	s_waitcnt vmcnt(46)
	v_mfma_f32_16x16x32_bf16 v[2:5], v[108:111], v[112:115], v[2:5]
	global_load_dwordx4 v[108:111], v[56:57], off offset:1920
	global_load_dwordx4 v[112:115], v[58:59], off offset:1920
	s_waitcnt vmcnt(46)
	v_mfma_f32_16x16x32_bf16 v[2:5], v[116:119], v[120:123], v[2:5]
	global_load_dwordx4 v[116:119], v[56:57], off offset:1984
	global_load_dwordx4 v[120:123], v[58:59], off offset:1984
	s_waitcnt vmcnt(46)
	v_mfma_f32_16x16x32_bf16 v[2:5], v[124:127], v[128:131], v[2:5]
	global_load_dwordx4 v[124:127], v[56:57], off offset:2048
	global_load_dwordx4 v[128:131], v[58:59], off offset:2048
	s_waitcnt vmcnt(46)
	v_mfma_f32_16x16x32_bf16 v[2:5], v[132:135], v[136:139], v[2:5]
	global_load_dwordx4 v[132:135], v[56:57], off offset:2112
	global_load_dwordx4 v[136:139], v[58:59], off offset:2112
	s_waitcnt vmcnt(46)
	v_mfma_f32_16x16x32_bf16 v[2:5], v[140:143], v[144:147], v[2:5]
	global_load_dwordx4 v[140:143], v[56:57], off offset:2176
	global_load_dwordx4 v[144:147], v[58:59], off offset:2176
	s_waitcnt vmcnt(46)
	v_mfma_f32_16x16x32_bf16 v[2:5], v[148:151], v[152:155], v[2:5]
	global_load_dwordx4 v[148:151], v[56:57], off offset:2240
	global_load_dwordx4 v[152:155], v[58:59], off offset:2240
	s_waitcnt vmcnt(46)
	v_mfma_f32_16x16x32_bf16 v[2:5], v[156:159], v[160:163], v[2:5]
	global_load_dwordx4 v[156:159], v[56:57], off offset:2304
	global_load_dwordx4 v[160:163], v[58:59], off offset:2304
	s_waitcnt vmcnt(46)
	v_mfma_f32_16x16x32_bf16 v[2:5], v[164:167], v[168:171], v[2:5]
	global_load_dwordx4 v[164:167], v[56:57], off offset:2368
	global_load_dwordx4 v[168:171], v[58:59], off offset:2368
	s_waitcnt vmcnt(46)
	v_mfma_f32_16x16x32_bf16 v[2:5], v[172:175], v[176:179], v[2:5]
	global_load_dwordx4 v[172:175], v[56:57], off offset:2432
	global_load_dwordx4 v[176:179], v[58:59], off offset:2432
	s_waitcnt vmcnt(46)
	v_mfma_f32_16x16x32_bf16 v[2:5], v[180:183], v[184:187], v[2:5]
	global_load_dwordx4 v[180:183], v[56:57], off offset:2496
	global_load_dwordx4 v[184:187], v[58:59], off offset:2496
	s_waitcnt vmcnt(46)
	v_mfma_f32_16x16x32_bf16 v[2:5], v[188:191], v[192:195], v[2:5]
	global_load_dwordx4 v[188:191], v[56:57], off offset:2560
	global_load_dwordx4 v[192:195], v[58:59], off offset:2560
	s_waitcnt vmcnt(46)
	v_mfma_f32_16x16x32_bf16 v[2:5], v[196:199], v[200:203], v[2:5]
	global_load_dwordx4 v[196:199], v[56:57], off offset:2624
	global_load_dwordx4 v[200:203], v[58:59], off offset:2624
	s_waitcnt vmcnt(46)
	v_mfma_f32_16x16x32_bf16 v[2:5], v[204:207], v[208:211], v[2:5]
	global_load_dwordx4 v[204:207], v[56:57], off offset:2688
	global_load_dwordx4 v[208:211], v[58:59], off offset:2688
	s_waitcnt vmcnt(46)
	v_mfma_f32_16x16x32_bf16 v[2:5], v[212:215], v[216:219], v[2:5]
	global_load_dwordx4 v[212:215], v[56:57], off offset:2752
	global_load_dwordx4 v[216:219], v[58:59], off offset:2752
	s_waitcnt vmcnt(46)
	v_mfma_f32_16x16x32_bf16 v[2:5], v[220:223], v[224:227], v[2:5]
	global_load_dwordx4 v[220:223], v[56:57], off offset:2816
	global_load_dwordx4 v[224:227], v[58:59], off offset:2816
	s_waitcnt vmcnt(46)
	v_mfma_f32_16x16x32_bf16 v[2:5], v[228:231], v[232:235], v[2:5]
	global_load_dwordx4 v[228:231], v[56:57], off offset:2880
	global_load_dwordx4 v[232:235], v[58:59], off offset:2880
	s_waitcnt vmcnt(46)
	v_mfma_f32_16x16x32_bf16 v[2:5], v[236:239], v[240:243], v[2:5]
	global_load_dwordx4 v[236:239], v[56:57], off offset:2944
	global_load_dwordx4 v[240:243], v[58:59], off offset:2944
	s_waitcnt vmcnt(46)
; template <int ph>
; __device__ __forceinline__ void run_phase(KPtr kp, unsigned char* shm) {
;     ...
; #pragma unroll 8
;                     for (int ks = 0; ks < 64; ++ks) a4 = __builtin_amdgcn_mfma_f32_16x16x32_bf16(*(const bf16x8*)(ap + ks * 32), *(const bf16x8*)(bp + ks * 32), a4, 0, 0, 0);
	v_mfma_f32_16x16x32_bf16 v[2:5], v[244:247], v[248:251], v[2:5]
	global_load_dwordx4 v[244:247], v[56:57], off offset:3008
	global_load_dwordx4 v[248:251], v[58:59], off offset:3008
	s_waitcnt vmcnt(46)
	v_mfma_f32_16x16x32_bf16 v[2:5], v[60:63], v[64:67], v[2:5]
	global_load_dwordx4 v[60:63], v[56:57], off offset:3072
	global_load_dwordx4 v[64:67], v[58:59], off offset:3072
	s_waitcnt vmcnt(46)
	v_mfma_f32_16x16x32_bf16 v[2:5], v[68:71], v[72:75], v[2:5]
	global_load_dwordx4 v[68:71], v[56:57], off offset:3136
	global_load_dwordx4 v[72:75], v[58:59], off offset:3136
	s_waitcnt vmcnt(46)
	v_mfma_f32_16x16x32_bf16 v[2:5], v[76:79], v[80:83], v[2:5]
	global_load_dwordx4 v[76:79], v[56:57], off offset:3200
	global_load_dwordx4 v[80:83], v[58:59], off offset:3200
	s_waitcnt vmcnt(46)
	v_mfma_f32_16x16x32_bf16 v[2:5], v[84:87], v[88:91], v[2:5]
	global_load_dwordx4 v[84:87], v[56:57], off offset:3264
	global_load_dwordx4 v[88:91], v[58:59], off offset:3264
	s_waitcnt vmcnt(46)
	v_mfma_f32_16x16x32_bf16 v[2:5], v[92:95], v[96:99], v[2:5]
	global_load_dwordx4 v[92:95], v[56:57], off offset:3328
	global_load_dwordx4 v[96:99], v[58:59], off offset:3328
	s_waitcnt vmcnt(46)
	v_mfma_f32_16x16x32_bf16 v[2:5], v[100:103], v[104:107], v[2:5]
	global_load_dwordx4 v[100:103], v[56:57], off offset:3392
	global_load_dwordx4 v[104:107], v[58:59], off offset:3392
	s_waitcnt vmcnt(46)
	v_mfma_f32_16x16x32_bf16 v[2:5], v[108:111], v[112:115], v[2:5]
	global_load_dwordx4 v[108:111], v[56:57], off offset:3456
	global_load_dwordx4 v[112:115], v[58:59], off offset:3456
	s_waitcnt vmcnt(46)
	v_mfma_f32_16x16x32_bf16 v[2:5], v[116:119], v[120:123], v[2:5]
	global_load_dwordx4 v[116:119], v[56:57], off offset:3520
	global_load_dwordx4 v[120:123], v[58:59], off offset:3520
	s_waitcnt vmcnt(46)
	v_mfma_f32_16x16x32_bf16 v[2:5], v[124:127], v[128:131], v[2:5]
	global_load_dwordx4 v[124:127], v[56:57], off offset:3584
	global_load_dwordx4 v[128:131], v[58:59], off offset:3584
	s_waitcnt vmcnt(46)
	v_mfma_f32_16x16x32_bf16 v[2:5], v[132:135], v[136:139], v[2:5]
	global_load_dwordx4 v[132:135], v[56:57], off offset:3648
	global_load_dwordx4 v[136:139], v[58:59], off offset:3648
	s_waitcnt vmcnt(46)
	v_mfma_f32_16x16x32_bf16 v[2:5], v[140:143], v[144:147], v[2:5]
	global_load_dwordx4 v[140:143], v[56:57], off offset:3712
	global_load_dwordx4 v[144:147], v[58:59], off offset:3712
	s_waitcnt vmcnt(46)
	v_mfma_f32_16x16x32_bf16 v[2:5], v[148:151], v[152:155], v[2:5]
	global_load_dwordx4 v[148:151], v[56:57], off offset:3776
	global_load_dwordx4 v[152:155], v[58:59], off offset:3776
	s_waitcnt vmcnt(46)
	v_mfma_f32_16x16x32_bf16 v[2:5], v[156:159], v[160:163], v[2:5]
	global_load_dwordx4 v[156:159], v[56:57], off offset:3840
	global_load_dwordx4 v[160:163], v[58:59], off offset:3840
	s_waitcnt vmcnt(46)
	v_mfma_f32_16x16x32_bf16 v[2:5], v[164:167], v[168:171], v[2:5]
	global_load_dwordx4 v[164:167], v[56:57], off offset:3904
	global_load_dwordx4 v[168:171], v[58:59], off offset:3904
	s_waitcnt vmcnt(46)
	v_mfma_f32_16x16x32_bf16 v[2:5], v[172:175], v[176:179], v[2:5]
	global_load_dwordx4 v[172:175], v[56:57], off offset:3968
	global_load_dwordx4 v[176:179], v[58:59], off offset:3968
	s_waitcnt vmcnt(46)
	v_mfma_f32_16x16x32_bf16 v[2:5], v[180:183], v[184:187], v[2:5]
	global_load_dwordx4 v[180:183], v[56:57], off offset:4032
	global_load_dwordx4 v[184:187], v[58:59], off offset:4032
	s_waitcnt vmcnt(46)
	v_mfma_f32_16x16x32_bf16 v[2:5], v[188:191], v[192:195], v[2:5]
	s_waitcnt vmcnt(44)
	v_mfma_f32_16x16x32_bf16 v[2:5], v[196:199], v[200:203], v[2:5]
	s_waitcnt vmcnt(42)
	v_mfma_f32_16x16x32_bf16 v[2:5], v[204:207], v[208:211], v[2:5]
	s_waitcnt vmcnt(40)
	v_mfma_f32_16x16x32_bf16 v[2:5], v[212:215], v[216:219], v[2:5]
	s_waitcnt vmcnt(38)
	v_mfma_f32_16x16x32_bf16 v[2:5], v[220:223], v[224:227], v[2:5]
	s_waitcnt vmcnt(36)
	v_mfma_f32_16x16x32_bf16 v[2:5], v[228:231], v[232:235], v[2:5]
	s_waitcnt vmcnt(34)
	v_mfma_f32_16x16x32_bf16 v[2:5], v[236:239], v[240:243], v[2:5]
	s_waitcnt vmcnt(32)
	v_mfma_f32_16x16x32_bf16 v[2:5], v[244:247], v[248:251], v[2:5]
	s_waitcnt vmcnt(30)
	v_mfma_f32_16x16x32_bf16 v[2:5], v[60:63], v[64:67], v[2:5]
	s_waitcnt vmcnt(28)
	v_mfma_f32_16x16x32_bf16 v[2:5], v[68:71], v[72:75], v[2:5]
	s_waitcnt vmcnt(26)
	v_mfma_f32_16x16x32_bf16 v[2:5], v[76:79], v[80:83], v[2:5]
	s_waitcnt vmcnt(24)
	v_mfma_f32_16x16x32_bf16 v[2:5], v[84:87], v[88:91], v[2:5]
	s_waitcnt vmcnt(22)
	v_mfma_f32_16x16x32_bf16 v[2:5], v[92:95], v[96:99], v[2:5]
	s_waitcnt vmcnt(20)
	v_mfma_f32_16x16x32_bf16 v[2:5], v[100:103], v[104:107], v[2:5]
	s_waitcnt vmcnt(18)
	v_mfma_f32_16x16x32_bf16 v[2:5], v[108:111], v[112:115], v[2:5]
	s_waitcnt vmcnt(16)
	v_mfma_f32_16x16x32_bf16 v[2:5], v[116:119], v[120:123], v[2:5]
	s_waitcnt vmcnt(14)
	v_mfma_f32_16x16x32_bf16 v[2:5], v[124:127], v[128:131], v[2:5]
	s_waitcnt vmcnt(12)
	v_mfma_f32_16x16x32_bf16 v[2:5], v[132:135], v[136:139], v[2:5]
	s_waitcnt vmcnt(10)
	v_mfma_f32_16x16x32_bf16 v[2:5], v[140:143], v[144:147], v[2:5]
	s_waitcnt vmcnt(8)
	v_mfma_f32_16x16x32_bf16 v[2:5], v[148:151], v[152:155], v[2:5]
	s_waitcnt vmcnt(6)
	v_mfma_f32_16x16x32_bf16 v[2:5], v[156:159], v[160:163], v[2:5]
	s_waitcnt vmcnt(4)
	v_mfma_f32_16x16x32_bf16 v[2:5], v[164:167], v[168:171], v[2:5]
	s_waitcnt vmcnt(2)
	v_mfma_f32_16x16x32_bf16 v[2:5], v[172:175], v[176:179], v[2:5]
	s_waitcnt vmcnt(0)
	v_mfma_f32_16x16x32_bf16 v[2:5], v[180:183], v[184:187], v[2:5]
	s_branch .Lc10_ret
	.p2align 11
